# merge epilogue: 8 brg reloads pipelined 4-deep through v232-247 (global_load + counted vmcnt) instead of serial flat_load/vmcnt(0)
# speedup vs baseline: 1.0070x; 1.0070x over previous
; DEVI float bf2f(unsigned u) { return __uint_as_float(u << 16); }
; DEVI float sigmoidf(float x) { return 1.f / (1.f + __expf(-x)); }
; DEVI void phase_merge(const Params& p, char* smem) {
;     ...
; #pragma unroll
;       for (int m = 0; m < 4; ++m)
; #pragma unroll
;         for (int n = 0; n < 4; ++n) {
;           const u32x4 bq = brg[(m * 2 + (n >> 1)) * 256];
;           const unsigned b0 = bq[(n & 1) * 2], b1 = bq[(n & 1) * 2 + 1];
;           res[m][n][0] += sigmoidf(acc[m][n][0]) * bf2f(b0 & 0xffffu);
;           res[m][n][1] += sigmoidf(acc[m][n][1]) * __uint_as_float(b0 & 0xffff0000u);
;           res[m][n][2] += sigmoidf(acc[m][n][2]) * bf2f(b1 & 0xffffu);
;           res[m][n][3] += sigmoidf(acc[m][n][3]) * __uint_as_float(b1 & 0xffff0000u);
;         }
.LBB0_1424:
	global_load_dwordx4 v[232:235], v[70:71], off
	global_load_dwordx4 v[236:239], v[74:75], off
	global_load_dwordx4 v[240:243], v[76:77], off
	global_load_dwordx4 v[244:247], v[78:79], off
	v_mul_f32_e32 v0, 0xbfb8aa3b, v62
	v_exp_f32_e32 v62, v0
	v_mul_f32_e32 v0, 0xbfb8aa3b, v63
	v_exp_f32_e32 v63, v0
	s_add_i32 s82, s82, 1
	s_cmp_eq_u32 s82, 3
	v_pk_add_f32 v[62:63], v[62:63], 1.0 op_sel_hi:[1,0]
	s_nop 0
	v_div_scale_f32 v0, s[6:7], v63, v63, 1.0
	v_rcp_f32_e32 v124, v0
	s_nop 0
	v_fma_f32 v191, -v0, v124, 1.0
	v_fmac_f32_e32 v124, v191, v124
	v_div_scale_f32 v191, vcc, 1.0, v63, 1.0
	v_mul_f32_e32 v192, v191, v124
	v_fma_f32 v193, -v0, v192, v191
	v_fmac_f32_e32 v192, v193, v124
	v_fma_f32 v0, -v0, v192, v191
	v_div_fmas_f32 v0, v0, v124, v192
	v_div_fixup_f32 v63, v0, v63, 1.0
	v_div_scale_f32 v0, s[6:7], v62, v62, 1.0
	v_rcp_f32_e32 v124, v0
	s_nop 0
	v_fma_f32 v191, -v0, v124, 1.0
	v_fmac_f32_e32 v124, v191, v124
	v_div_scale_f32 v191, vcc, 1.0, v62, 1.0
	v_mul_f32_e32 v192, v191, v124
	v_fma_f32 v193, -v0, v192, v191
	v_fmac_f32_e32 v192, v193, v124
	v_fma_f32 v0, -v0, v192, v191
	v_div_fmas_f32 v0, v0, v124, v192
	v_div_fixup_f32 v62, v0, v62, 1.0
	v_mul_f32_e32 v0, 0xbfb8aa3b, v64
	s_waitcnt vmcnt(3) lgkmcnt(0)
	v_lshlrev_b32_e32 v192, 16, v232
	v_and_b32_e32 v193, 0xffff0000, v232
	v_pk_fma_f32 v[150:151], v[62:63], v[192:193], v[150:151]
	v_exp_f32_e32 v62, v0
	v_mul_f32_e32 v0, 0xbfb8aa3b, v65
	v_exp_f32_e32 v63, v0
	s_nop 0
	v_pk_add_f32 v[62:63], v[62:63], 1.0 op_sel_hi:[1,0]
	s_nop 0
	v_div_scale_f32 v0, s[6:7], v63, v63, 1.0
	v_rcp_f32_e32 v64, v0
	s_nop 0
	v_fma_f32 v65, -v0, v64, 1.0
	v_fmac_f32_e32 v64, v65, v64
	v_div_scale_f32 v65, vcc, 1.0, v63, 1.0
	v_mul_f32_e32 v66, v65, v64
	v_fma_f32 v124, -v0, v66, v65
	v_fmac_f32_e32 v66, v124, v64
	v_fma_f32 v0, -v0, v66, v65
	v_div_fmas_f32 v0, v0, v64, v66
	v_div_fixup_f32 v63, v0, v63, 1.0
	v_div_scale_f32 v0, s[6:7], v62, v62, 1.0
	v_rcp_f32_e32 v64, v0
	s_nop 0
	v_fma_f32 v65, -v0, v64, 1.0
	v_fmac_f32_e32 v64, v65, v64
	v_div_scale_f32 v65, vcc, 1.0, v62, 1.0
	v_mul_f32_e32 v66, v65, v64
	v_fma_f32 v124, -v0, v66, v65
	v_fmac_f32_e32 v66, v124, v64
	v_fma_f32 v0, -v0, v66, v65
	v_div_fmas_f32 v0, v0, v64, v66
	v_div_fixup_f32 v62, v0, v62, 1.0
	v_mul_f32_e32 v0, 0xbfb8aa3b, v58
	v_exp_f32_e32 v58, v0
	v_mul_f32_e32 v0, 0xbfb8aa3b, v59
	v_exp_f32_e32 v59, v0
	v_lshlrev_b32_e32 v64, 16, v233
	v_and_b32_e32 v65, 0xffff0000, v233
	v_pk_fma_f32 v[152:153], v[62:63], v[64:65], v[152:153]
	v_pk_add_f32 v[58:59], v[58:59], 1.0 op_sel_hi:[1,0]
	s_nop 0
	v_div_scale_f32 v0, s[6:7], v59, v59, 1.0
	v_rcp_f32_e32 v62, v0
	s_nop 0
	v_fma_f32 v63, -v0, v62, 1.0
	v_fmac_f32_e32 v62, v63, v62
	v_div_scale_f32 v63, vcc, 1.0, v59, 1.0
	v_mul_f32_e32 v64, v63, v62
	v_fma_f32 v65, -v0, v64, v63
	v_fmac_f32_e32 v64, v65, v62
	v_fma_f32 v0, -v0, v64, v63
	v_div_fmas_f32 v0, v0, v62, v64
	v_div_fixup_f32 v59, v0, v59, 1.0
	v_div_scale_f32 v0, s[6:7], v58, v58, 1.0
	v_rcp_f32_e32 v62, v0
	s_nop 0
	v_fma_f32 v63, -v0, v62, 1.0
	v_fmac_f32_e32 v62, v63, v62
	v_div_scale_f32 v63, vcc, 1.0, v58, 1.0
	v_mul_f32_e32 v64, v63, v62
	v_fma_f32 v65, -v0, v64, v63
	v_fmac_f32_e32 v64, v65, v62
	v_fma_f32 v0, -v0, v64, v63
	v_div_fmas_f32 v0, v0, v62, v64
	v_div_fixup_f32 v58, v0, v58, 1.0
	v_lshlrev_b32_e32 v62, 16, v234
	v_and_b32_e32 v63, 0xffff0000, v234
	v_mul_f32_e32 v0, 0xbfb8aa3b, v60
	v_pk_fma_f32 v[146:147], v[58:59], v[62:63], v[146:147]
	v_exp_f32_e32 v58, v0
	v_mul_f32_e32 v0, 0xbfb8aa3b, v61
	v_exp_f32_e32 v59, v0
	s_nop 0
	v_pk_add_f32 v[58:59], v[58:59], 1.0 op_sel_hi:[1,0]
	s_nop 0
	v_div_scale_f32 v0, s[6:7], v59, v59, 1.0
	v_rcp_f32_e32 v60, v0
	s_nop 0
	v_fma_f32 v61, -v0, v60, 1.0
	v_fmac_f32_e32 v60, v61, v60
	v_div_scale_f32 v61, vcc, 1.0, v59, 1.0
	v_mul_f32_e32 v62, v61, v60
	v_fma_f32 v63, -v0, v62, v61
	v_fmac_f32_e32 v62, v63, v60
	v_fma_f32 v0, -v0, v62, v61
	v_div_fmas_f32 v0, v0, v60, v62
	v_div_fixup_f32 v59, v0, v59, 1.0
	v_div_scale_f32 v0, s[6:7], v58, v58, 1.0
	v_rcp_f32_e32 v60, v0
	s_nop 0
	v_fma_f32 v61, -v0, v60, 1.0
	v_fmac_f32_e32 v60, v61, v60
	v_div_scale_f32 v61, vcc, 1.0, v58, 1.0
	v_mul_f32_e32 v62, v61, v60
	v_fma_f32 v63, -v0, v62, v61
	v_fmac_f32_e32 v62, v63, v60
	v_fma_f32 v0, -v0, v62, v61
	v_div_fmas_f32 v0, v0, v60, v62
	v_div_fixup_f32 v58, v0, v58, 1.0
	v_lshlrev_b32_e32 v60, 16, v235
	v_and_b32_e32 v61, 0xffff0000, v235
	v_pk_fma_f32 v[148:149], v[58:59], v[60:61], v[148:149]
	global_load_dwordx4 v[232:235], v[80:81], off
	v_mul_f32_e32 v0, 0xbfb8aa3b, v54
	v_exp_f32_e32 v54, v0
	v_mul_f32_e32 v0, 0xbfb8aa3b, v55
	v_exp_f32_e32 v55, v0
	s_nop 0
	v_pk_add_f32 v[54:55], v[54:55], 1.0 op_sel_hi:[1,0]
	s_nop 0
	v_div_scale_f32 v0, s[6:7], v55, v55, 1.0
	v_rcp_f32_e32 v62, v0
	s_nop 0
	v_fma_f32 v63, -v0, v62, 1.0
	v_fmac_f32_e32 v62, v63, v62
	v_div_scale_f32 v63, vcc, 1.0, v55, 1.0
	v_mul_f32_e32 v64, v63, v62
	v_fma_f32 v65, -v0, v64, v63
	v_fmac_f32_e32 v64, v65, v62
	v_fma_f32 v0, -v0, v64, v63
	v_div_fmas_f32 v0, v0, v62, v64
	v_div_fixup_f32 v55, v0, v55, 1.0
	v_div_scale_f32 v0, s[6:7], v54, v54, 1.0
	v_rcp_f32_e32 v62, v0
	s_nop 0
	v_fma_f32 v63, -v0, v62, 1.0
	v_fmac_f32_e32 v62, v63, v62
	v_div_scale_f32 v63, vcc, 1.0, v54, 1.0
	v_mul_f32_e32 v64, v63, v62
	v_fma_f32 v65, -v0, v64, v63
	v_fmac_f32_e32 v64, v65, v62
	v_fma_f32 v0, -v0, v64, v63
	v_div_fmas_f32 v0, v0, v62, v64
	v_div_fixup_f32 v54, v0, v54, 1.0
	v_mul_f32_e32 v0, 0xbfb8aa3b, v56
	s_waitcnt vmcnt(3) lgkmcnt(0)
; DEVI float bf2f(unsigned u) { return __uint_as_float(u << 16); }
; DEVI float sigmoidf(float x) { return 1.f / (1.f + __expf(-x)); }
; DEVI void phase_merge(const Params& p, char* smem) {
;     ...
; #pragma unroll
;       for (int m = 0; m < 4; ++m)
; #pragma unroll
;         for (int n = 0; n < 4; ++n) {
;           const u32x4 bq = brg[(m * 2 + (n >> 1)) * 256];
;           const unsigned b0 = bq[(n & 1) * 2], b1 = bq[(n & 1) * 2 + 1];
;           res[m][n][0] += sigmoidf(acc[m][n][0]) * bf2f(b0 & 0xffffu);
;           res[m][n][1] += sigmoidf(acc[m][n][1]) * __uint_as_float(b0 & 0xffff0000u);
;           res[m][n][2] += sigmoidf(acc[m][n][2]) * bf2f(b1 & 0xffffu);
;           res[m][n][3] += sigmoidf(acc[m][n][3]) * __uint_as_float(b1 & 0xffff0000u);
;         }
	v_lshlrev_b32_e32 v62, 16, v236
	v_and_b32_e32 v63, 0xffff0000, v236
	v_pk_fma_f32 v[142:143], v[54:55], v[62:63], v[142:143]
	v_exp_f32_e32 v54, v0
	v_mul_f32_e32 v0, 0xbfb8aa3b, v57
	v_exp_f32_e32 v55, v0
	s_nop 0
	v_pk_add_f32 v[54:55], v[54:55], 1.0 op_sel_hi:[1,0]
	s_nop 0
	v_div_scale_f32 v0, s[6:7], v55, v55, 1.0
	v_rcp_f32_e32 v56, v0
	s_nop 0
	v_fma_f32 v57, -v0, v56, 1.0
	v_fmac_f32_e32 v56, v57, v56
	v_div_scale_f32 v57, vcc, 1.0, v55, 1.0
	v_mul_f32_e32 v58, v57, v56
	v_fma_f32 v62, -v0, v58, v57
	v_fmac_f32_e32 v58, v62, v56
	v_fma_f32 v0, -v0, v58, v57
	v_div_fmas_f32 v0, v0, v56, v58
	v_div_fixup_f32 v55, v0, v55, 1.0
	v_div_scale_f32 v0, s[6:7], v54, v54, 1.0
	v_rcp_f32_e32 v56, v0
	s_nop 0
	v_fma_f32 v57, -v0, v56, 1.0
	v_fmac_f32_e32 v56, v57, v56
	v_div_scale_f32 v57, vcc, 1.0, v54, 1.0
	v_mul_f32_e32 v58, v57, v56
	v_fma_f32 v62, -v0, v58, v57
	v_fmac_f32_e32 v58, v62, v56
	v_fma_f32 v0, -v0, v58, v57
	v_div_fmas_f32 v0, v0, v56, v58
	v_div_fixup_f32 v54, v0, v54, 1.0
	v_mul_f32_e32 v0, 0xbfb8aa3b, v50
	v_exp_f32_e32 v50, v0
	v_mul_f32_e32 v0, 0xbfb8aa3b, v51
	v_exp_f32_e32 v51, v0
	v_lshlrev_b32_e32 v56, 16, v237
	v_and_b32_e32 v57, 0xffff0000, v237
	v_pk_fma_f32 v[144:145], v[54:55], v[56:57], v[144:145]
	v_pk_add_f32 v[50:51], v[50:51], 1.0 op_sel_hi:[1,0]
	s_nop 0
	v_div_scale_f32 v0, s[6:7], v51, v51, 1.0
	v_rcp_f32_e32 v54, v0
	s_nop 0
	v_fma_f32 v55, -v0, v54, 1.0
	v_fmac_f32_e32 v54, v55, v54
	v_div_scale_f32 v55, vcc, 1.0, v51, 1.0
	v_mul_f32_e32 v56, v55, v54
	v_fma_f32 v57, -v0, v56, v55
	v_fmac_f32_e32 v56, v57, v54
	v_fma_f32 v0, -v0, v56, v55
	v_div_fmas_f32 v0, v0, v54, v56
	v_div_fixup_f32 v51, v0, v51, 1.0
	v_div_scale_f32 v0, s[6:7], v50, v50, 1.0
	v_rcp_f32_e32 v54, v0
	s_nop 0
	v_fma_f32 v55, -v0, v54, 1.0
	v_fmac_f32_e32 v54, v55, v54
	v_div_scale_f32 v55, vcc, 1.0, v50, 1.0
	v_mul_f32_e32 v56, v55, v54
	v_fma_f32 v57, -v0, v56, v55
	v_fmac_f32_e32 v56, v57, v54
	v_fma_f32 v0, -v0, v56, v55
	v_div_fmas_f32 v0, v0, v54, v56
	v_div_fixup_f32 v50, v0, v50, 1.0
	v_lshlrev_b32_e32 v54, 16, v238
	v_and_b32_e32 v55, 0xffff0000, v238
	v_mul_f32_e32 v0, 0xbfb8aa3b, v52
	v_pk_fma_f32 v[138:139], v[50:51], v[54:55], v[138:139]
	v_exp_f32_e32 v50, v0
	v_mul_f32_e32 v0, 0xbfb8aa3b, v53
	v_exp_f32_e32 v51, v0
	s_nop 0
	v_pk_add_f32 v[50:51], v[50:51], 1.0 op_sel_hi:[1,0]
	s_nop 0
	v_div_scale_f32 v0, s[6:7], v51, v51, 1.0
	v_rcp_f32_e32 v52, v0
	s_nop 0
	v_fma_f32 v53, -v0, v52, 1.0
	v_fmac_f32_e32 v52, v53, v52
	v_div_scale_f32 v53, vcc, 1.0, v51, 1.0
	v_mul_f32_e32 v54, v53, v52
	v_fma_f32 v55, -v0, v54, v53
	v_fmac_f32_e32 v54, v55, v52
	v_fma_f32 v0, -v0, v54, v53
	v_div_fmas_f32 v0, v0, v52, v54
	v_div_fixup_f32 v51, v0, v51, 1.0
	v_div_scale_f32 v0, s[6:7], v50, v50, 1.0
	v_rcp_f32_e32 v52, v0
	s_nop 0
	v_fma_f32 v53, -v0, v52, 1.0
	v_fmac_f32_e32 v52, v53, v52
	v_div_scale_f32 v53, vcc, 1.0, v50, 1.0
	v_mul_f32_e32 v54, v53, v52
	v_fma_f32 v55, -v0, v54, v53
	v_fmac_f32_e32 v54, v55, v52
	v_fma_f32 v0, -v0, v54, v53
	v_div_fmas_f32 v0, v0, v52, v54
	v_div_fixup_f32 v50, v0, v50, 1.0
	v_lshlrev_b32_e32 v52, 16, v239
	v_and_b32_e32 v53, 0xffff0000, v239
	v_pk_fma_f32 v[140:141], v[50:51], v[52:53], v[140:141]
	global_load_dwordx4 v[236:239], v[82:83], off
	v_mul_f32_e32 v0, 0xbfb8aa3b, v46
	v_exp_f32_e32 v46, v0
	v_mul_f32_e32 v0, 0xbfb8aa3b, v47
	v_exp_f32_e32 v47, v0
	s_nop 0
	v_pk_add_f32 v[46:47], v[46:47], 1.0 op_sel_hi:[1,0]
	s_nop 0
	v_div_scale_f32 v0, s[6:7], v47, v47, 1.0
	v_rcp_f32_e32 v54, v0
	s_nop 0
	v_fma_f32 v55, -v0, v54, 1.0
	v_fmac_f32_e32 v54, v55, v54
	v_div_scale_f32 v55, vcc, 1.0, v47, 1.0
	v_mul_f32_e32 v56, v55, v54
	v_fma_f32 v57, -v0, v56, v55
	v_fmac_f32_e32 v56, v57, v54
	v_fma_f32 v0, -v0, v56, v55
	v_div_fmas_f32 v0, v0, v54, v56
	v_div_fixup_f32 v47, v0, v47, 1.0
	v_div_scale_f32 v0, s[6:7], v46, v46, 1.0
	v_rcp_f32_e32 v54, v0
	s_nop 0
	v_fma_f32 v55, -v0, v54, 1.0
	v_fmac_f32_e32 v54, v55, v54
	v_div_scale_f32 v55, vcc, 1.0, v46, 1.0
	v_mul_f32_e32 v56, v55, v54
	v_fma_f32 v57, -v0, v56, v55
	v_fmac_f32_e32 v56, v57, v54
	v_fma_f32 v0, -v0, v56, v55
	v_div_fmas_f32 v0, v0, v54, v56
	v_div_fixup_f32 v46, v0, v46, 1.0
	v_mul_f32_e32 v0, 0xbfb8aa3b, v48
	s_waitcnt vmcnt(3) lgkmcnt(0)
	v_lshlrev_b32_e32 v54, 16, v240
	v_and_b32_e32 v55, 0xffff0000, v240
	v_pk_fma_f32 v[134:135], v[46:47], v[54:55], v[134:135]
	v_exp_f32_e32 v46, v0
	v_mul_f32_e32 v0, 0xbfb8aa3b, v49
	v_exp_f32_e32 v47, v0
	s_nop 0
	v_pk_add_f32 v[46:47], v[46:47], 1.0 op_sel_hi:[1,0]
	s_nop 0
	v_div_scale_f32 v0, s[6:7], v47, v47, 1.0
	v_rcp_f32_e32 v48, v0
	s_nop 0
	v_fma_f32 v49, -v0, v48, 1.0
	v_fmac_f32_e32 v48, v49, v48
	v_div_scale_f32 v49, vcc, 1.0, v47, 1.0
	v_mul_f32_e32 v50, v49, v48
	v_fma_f32 v54, -v0, v50, v49
	v_fmac_f32_e32 v50, v54, v48
	v_fma_f32 v0, -v0, v50, v49
	v_div_fmas_f32 v0, v0, v48, v50
	v_div_fixup_f32 v47, v0, v47, 1.0
	v_div_scale_f32 v0, s[6:7], v46, v46, 1.0
	v_rcp_f32_e32 v48, v0
	s_nop 0
	v_fma_f32 v49, -v0, v48, 1.0
	v_fmac_f32_e32 v48, v49, v48
	v_div_scale_f32 v49, vcc, 1.0, v46, 1.0
	v_mul_f32_e32 v50, v49, v48
	v_fma_f32 v54, -v0, v50, v49
	v_fmac_f32_e32 v50, v54, v48
	v_fma_f32 v0, -v0, v50, v49
	v_div_fmas_f32 v0, v0, v48, v50
	v_div_fixup_f32 v46, v0, v46, 1.0
	v_mul_f32_e32 v0, 0xbfb8aa3b, v42
	v_exp_f32_e32 v42, v0
	v_mul_f32_e32 v0, 0xbfb8aa3b, v43
	v_exp_f32_e32 v43, v0
	v_lshlrev_b32_e32 v48, 16, v241
	v_and_b32_e32 v49, 0xffff0000, v241
	v_pk_fma_f32 v[136:137], v[46:47], v[48:49], v[136:137]
	v_pk_add_f32 v[42:43], v[42:43], 1.0 op_sel_hi:[1,0]
	s_nop 0
	v_div_scale_f32 v0, s[6:7], v43, v43, 1.0
	v_rcp_f32_e32 v46, v0
	s_nop 0
	v_fma_f32 v47, -v0, v46, 1.0
; DEVI float bf2f(unsigned u) { return __uint_as_float(u << 16); }
; DEVI float sigmoidf(float x) { return 1.f / (1.f + __expf(-x)); }
; DEVI void phase_merge(const Params& p, char* smem) {
;     ...
; #pragma unroll
;       for (int m = 0; m < 4; ++m)
; #pragma unroll
;         for (int n = 0; n < 4; ++n) {
;           const u32x4 bq = brg[(m * 2 + (n >> 1)) * 256];
;           const unsigned b0 = bq[(n & 1) * 2], b1 = bq[(n & 1) * 2 + 1];
;           res[m][n][0] += sigmoidf(acc[m][n][0]) * bf2f(b0 & 0xffffu);
;           res[m][n][1] += sigmoidf(acc[m][n][1]) * __uint_as_float(b0 & 0xffff0000u);
;           res[m][n][2] += sigmoidf(acc[m][n][2]) * bf2f(b1 & 0xffffu);
;           res[m][n][3] += sigmoidf(acc[m][n][3]) * __uint_as_float(b1 & 0xffff0000u);
;         }
	v_fmac_f32_e32 v46, v47, v46
	v_div_scale_f32 v47, vcc, 1.0, v43, 1.0
	v_mul_f32_e32 v48, v47, v46
	v_fma_f32 v49, -v0, v48, v47
	v_fmac_f32_e32 v48, v49, v46
	v_fma_f32 v0, -v0, v48, v47
	v_div_fmas_f32 v0, v0, v46, v48
	v_div_fixup_f32 v43, v0, v43, 1.0
	v_div_scale_f32 v0, s[6:7], v42, v42, 1.0
	v_rcp_f32_e32 v46, v0
	s_nop 0
	v_fma_f32 v47, -v0, v46, 1.0
	v_fmac_f32_e32 v46, v47, v46
	v_div_scale_f32 v47, vcc, 1.0, v42, 1.0
	v_mul_f32_e32 v48, v47, v46
	v_fma_f32 v49, -v0, v48, v47
	v_fmac_f32_e32 v48, v49, v46
	v_fma_f32 v0, -v0, v48, v47
	v_div_fmas_f32 v0, v0, v46, v48
	v_div_fixup_f32 v42, v0, v42, 1.0
	v_lshlrev_b32_e32 v46, 16, v242
	v_and_b32_e32 v47, 0xffff0000, v242
	v_mul_f32_e32 v0, 0xbfb8aa3b, v44
	v_pk_fma_f32 v[130:131], v[42:43], v[46:47], v[130:131]
	v_exp_f32_e32 v42, v0
	v_mul_f32_e32 v0, 0xbfb8aa3b, v45
	v_exp_f32_e32 v43, v0
	s_nop 0
	v_pk_add_f32 v[42:43], v[42:43], 1.0 op_sel_hi:[1,0]
	s_nop 0
	v_div_scale_f32 v0, s[6:7], v43, v43, 1.0
	v_rcp_f32_e32 v44, v0
	s_nop 0
	v_fma_f32 v45, -v0, v44, 1.0
	v_fmac_f32_e32 v44, v45, v44
	v_div_scale_f32 v45, vcc, 1.0, v43, 1.0
	v_mul_f32_e32 v46, v45, v44
	v_fma_f32 v47, -v0, v46, v45
	v_fmac_f32_e32 v46, v47, v44
	v_fma_f32 v0, -v0, v46, v45
	v_div_fmas_f32 v0, v0, v44, v46
	v_div_fixup_f32 v43, v0, v43, 1.0
	v_div_scale_f32 v0, s[6:7], v42, v42, 1.0
	v_rcp_f32_e32 v44, v0
	s_nop 0
	v_fma_f32 v45, -v0, v44, 1.0
	v_fmac_f32_e32 v44, v45, v44
	v_div_scale_f32 v45, vcc, 1.0, v42, 1.0
	v_mul_f32_e32 v46, v45, v44
	v_fma_f32 v47, -v0, v46, v45
	v_fmac_f32_e32 v46, v47, v44
	v_fma_f32 v0, -v0, v46, v45
	v_div_fmas_f32 v0, v0, v44, v46
	v_div_fixup_f32 v42, v0, v42, 1.0
	v_lshlrev_b32_e32 v44, 16, v243
	v_and_b32_e32 v45, 0xffff0000, v243
	v_pk_fma_f32 v[132:133], v[42:43], v[44:45], v[132:133]
	global_load_dwordx4 v[240:243], v[72:73], off
	v_mul_f32_e32 v0, 0xbfb8aa3b, v38
	v_exp_f32_e32 v38, v0
	v_mul_f32_e32 v0, 0xbfb8aa3b, v39
	v_exp_f32_e32 v39, v0
	s_nop 0
	v_pk_add_f32 v[38:39], v[38:39], 1.0 op_sel_hi:[1,0]
	s_nop 0
	v_div_scale_f32 v0, s[6:7], v39, v39, 1.0
	v_rcp_f32_e32 v46, v0
	s_nop 0
	v_fma_f32 v47, -v0, v46, 1.0
	v_fmac_f32_e32 v46, v47, v46
	v_div_scale_f32 v47, vcc, 1.0, v39, 1.0
	v_mul_f32_e32 v48, v47, v46
	v_fma_f32 v49, -v0, v48, v47
	v_fmac_f32_e32 v48, v49, v46
	v_fma_f32 v0, -v0, v48, v47
	v_div_fmas_f32 v0, v0, v46, v48
	v_div_fixup_f32 v39, v0, v39, 1.0
	v_div_scale_f32 v0, s[6:7], v38, v38, 1.0
	v_rcp_f32_e32 v46, v0
	s_nop 0
	v_fma_f32 v47, -v0, v46, 1.0
	v_fmac_f32_e32 v46, v47, v46
	v_div_scale_f32 v47, vcc, 1.0, v38, 1.0
	v_mul_f32_e32 v48, v47, v46
	v_fma_f32 v49, -v0, v48, v47
	v_fmac_f32_e32 v48, v49, v46
	v_fma_f32 v0, -v0, v48, v47
	v_div_fmas_f32 v0, v0, v46, v48
	v_div_fixup_f32 v38, v0, v38, 1.0
	v_mul_f32_e32 v0, 0xbfb8aa3b, v40
	s_waitcnt vmcnt(3) lgkmcnt(0)
	v_lshlrev_b32_e32 v46, 16, v244
	v_and_b32_e32 v47, 0xffff0000, v244
	v_pk_fma_f32 v[126:127], v[38:39], v[46:47], v[126:127]
	v_exp_f32_e32 v38, v0
	v_mul_f32_e32 v0, 0xbfb8aa3b, v41
	v_exp_f32_e32 v39, v0
	s_nop 0
	v_pk_add_f32 v[38:39], v[38:39], 1.0 op_sel_hi:[1,0]
	s_nop 0
	v_div_scale_f32 v0, s[6:7], v39, v39, 1.0
	v_rcp_f32_e32 v40, v0
	s_nop 0
	v_fma_f32 v41, -v0, v40, 1.0
	v_fmac_f32_e32 v40, v41, v40
	v_div_scale_f32 v41, vcc, 1.0, v39, 1.0
	v_mul_f32_e32 v42, v41, v40
	v_fma_f32 v46, -v0, v42, v41
	v_fmac_f32_e32 v42, v46, v40
	v_fma_f32 v0, -v0, v42, v41
	v_div_fmas_f32 v0, v0, v40, v42
	v_div_fixup_f32 v39, v0, v39, 1.0
	v_div_scale_f32 v0, s[6:7], v38, v38, 1.0
	v_rcp_f32_e32 v40, v0
	s_nop 0
	v_fma_f32 v41, -v0, v40, 1.0
	v_fmac_f32_e32 v40, v41, v40
	v_div_scale_f32 v41, vcc, 1.0, v38, 1.0
	v_mul_f32_e32 v42, v41, v40
	v_fma_f32 v46, -v0, v42, v41
	v_fmac_f32_e32 v42, v46, v40
	v_fma_f32 v0, -v0, v42, v41
	v_div_fmas_f32 v0, v0, v40, v42
	v_div_fixup_f32 v38, v0, v38, 1.0
	v_mul_f32_e32 v0, 0xbfb8aa3b, v34
	v_exp_f32_e32 v34, v0
	v_mul_f32_e32 v0, 0xbfb8aa3b, v35
	v_exp_f32_e32 v35, v0
	v_lshlrev_b32_e32 v40, 16, v245
	v_and_b32_e32 v41, 0xffff0000, v245
	v_pk_fma_f32 v[128:129], v[38:39], v[40:41], v[128:129]
	v_pk_add_f32 v[34:35], v[34:35], 1.0 op_sel_hi:[1,0]
	s_nop 0
	v_div_scale_f32 v0, s[6:7], v35, v35, 1.0
	v_rcp_f32_e32 v38, v0
	s_nop 0
	v_fma_f32 v39, -v0, v38, 1.0
	v_fmac_f32_e32 v38, v39, v38
	v_div_scale_f32 v39, vcc, 1.0, v35, 1.0
	v_mul_f32_e32 v40, v39, v38
	v_fma_f32 v41, -v0, v40, v39
	v_fmac_f32_e32 v40, v41, v38
	v_fma_f32 v0, -v0, v40, v39
	v_div_fmas_f32 v0, v0, v38, v40
	v_div_fixup_f32 v35, v0, v35, 1.0
	v_div_scale_f32 v0, s[6:7], v34, v34, 1.0
	v_rcp_f32_e32 v38, v0
	s_nop 0
	v_fma_f32 v39, -v0, v38, 1.0
	v_fmac_f32_e32 v38, v39, v38
	v_div_scale_f32 v39, vcc, 1.0, v34, 1.0
	v_mul_f32_e32 v40, v39, v38
	v_fma_f32 v41, -v0, v40, v39
	v_fmac_f32_e32 v40, v41, v38
	v_fma_f32 v0, -v0, v40, v39
	v_div_fmas_f32 v0, v0, v38, v40
	v_div_fixup_f32 v34, v0, v34, 1.0
	v_lshlrev_b32_e32 v38, 16, v246
	v_and_b32_e32 v39, 0xffff0000, v246
	v_mul_f32_e32 v0, 0xbfb8aa3b, v36
	v_pk_fma_f32 v[118:119], v[34:35], v[38:39], v[118:119]
	v_exp_f32_e32 v34, v0
	v_mul_f32_e32 v0, 0xbfb8aa3b, v37
	v_exp_f32_e32 v35, v0
	s_nop 0
	v_pk_add_f32 v[34:35], v[34:35], 1.0 op_sel_hi:[1,0]
	s_nop 0
	v_div_scale_f32 v0, s[6:7], v35, v35, 1.0
	v_rcp_f32_e32 v36, v0
	s_nop 0
	v_fma_f32 v37, -v0, v36, 1.0
	v_fmac_f32_e32 v36, v37, v36
	v_div_scale_f32 v37, vcc, 1.0, v35, 1.0
	v_mul_f32_e32 v38, v37, v36
	v_fma_f32 v39, -v0, v38, v37
	v_fmac_f32_e32 v38, v39, v36
	v_fma_f32 v0, -v0, v38, v37
	v_div_fmas_f32 v0, v0, v36, v38
	v_div_fixup_f32 v35, v0, v35, 1.0
	v_div_scale_f32 v0, s[6:7], v34, v34, 1.0
	v_rcp_f32_e32 v36, v0
	s_nop 0
	v_fma_f32 v37, -v0, v36, 1.0
	v_fmac_f32_e32 v36, v37, v36
	v_div_scale_f32 v37, vcc, 1.0, v34, 1.0
	v_mul_f32_e32 v38, v37, v36
	v_fma_f32 v39, -v0, v38, v37
	v_fmac_f32_e32 v38, v39, v36
	v_fma_f32 v0, -v0, v38, v37
	v_div_fmas_f32 v0, v0, v36, v38
	v_div_fixup_f32 v34, v0, v34, 1.0
	v_lshlrev_b32_e32 v36, 16, v247
	v_and_b32_e32 v37, 0xffff0000, v247
	v_pk_fma_f32 v[120:121], v[34:35], v[36:37], v[120:121]
	global_load_dwordx4 v[244:247], v[84:85], off
	v_mul_f32_e32 v0, 0xbfb8aa3b, v30
	v_exp_f32_e32 v30, v0
	v_mul_f32_e32 v0, 0xbfb8aa3b, v31
	v_exp_f32_e32 v31, v0
	s_nop 0
	v_pk_add_f32 v[30:31], v[30:31], 1.0 op_sel_hi:[1,0]
	s_nop 0
	v_div_scale_f32 v0, s[6:7], v31, v31, 1.0
	v_rcp_f32_e32 v38, v0
	s_nop 0
	v_fma_f32 v39, -v0, v38, 1.0
	v_fmac_f32_e32 v38, v39, v38
	v_div_scale_f32 v39, vcc, 1.0, v31, 1.0
	v_mul_f32_e32 v40, v39, v38
	v_fma_f32 v41, -v0, v40, v39
	v_fmac_f32_e32 v40, v41, v38
	v_fma_f32 v0, -v0, v40, v39
	v_div_fmas_f32 v0, v0, v38, v40
	v_div_fixup_f32 v31, v0, v31, 1.0
	v_div_scale_f32 v0, s[6:7], v30, v30, 1.0
	v_rcp_f32_e32 v38, v0
	s_nop 0
	v_fma_f32 v39, -v0, v38, 1.0
	v_fmac_f32_e32 v38, v39, v38
	v_div_scale_f32 v39, vcc, 1.0, v30, 1.0
	v_mul_f32_e32 v40, v39, v38
	v_fma_f32 v41, -v0, v40, v39
	v_fmac_f32_e32 v40, v41, v38
	v_fma_f32 v0, -v0, v40, v39
	v_div_fmas_f32 v0, v0, v38, v40
	v_div_fixup_f32 v30, v0, v30, 1.0
	v_mul_f32_e32 v0, 0xbfb8aa3b, v32
	s_waitcnt vmcnt(3) lgkmcnt(0)
; DEVI float bf2f(unsigned u) { return __uint_as_float(u << 16); }
; DEVI float sigmoidf(float x) { return 1.f / (1.f + __expf(-x)); }
; DEVI void phase_merge(const Params& p, char* smem) {
;     ...
; #pragma unroll
;       for (int m = 0; m < 4; ++m)
; #pragma unroll
;         for (int n = 0; n < 4; ++n) {
;           const u32x4 bq = brg[(m * 2 + (n >> 1)) * 256];
;           const unsigned b0 = bq[(n & 1) * 2], b1 = bq[(n & 1) * 2 + 1];
;           res[m][n][0] += sigmoidf(acc[m][n][0]) * bf2f(b0 & 0xffffu);
;           res[m][n][1] += sigmoidf(acc[m][n][1]) * __uint_as_float(b0 & 0xffff0000u);
;           res[m][n][2] += sigmoidf(acc[m][n][2]) * bf2f(b1 & 0xffffu);
;           res[m][n][3] += sigmoidf(acc[m][n][3]) * __uint_as_float(b1 & 0xffff0000u);
;         }
	v_lshlrev_b32_e32 v38, 16, v232
	v_and_b32_e32 v39, 0xffff0000, v232
	v_pk_fma_f32 v[114:115], v[30:31], v[38:39], v[114:115]
	v_exp_f32_e32 v30, v0
	v_mul_f32_e32 v0, 0xbfb8aa3b, v33
	v_exp_f32_e32 v31, v0
	s_nop 0
	v_pk_add_f32 v[30:31], v[30:31], 1.0 op_sel_hi:[1,0]
	s_nop 0
	v_div_scale_f32 v0, s[6:7], v31, v31, 1.0
	v_rcp_f32_e32 v32, v0
	s_nop 0
	v_fma_f32 v33, -v0, v32, 1.0
	v_fmac_f32_e32 v32, v33, v32
	v_div_scale_f32 v33, vcc, 1.0, v31, 1.0
	v_mul_f32_e32 v34, v33, v32
	v_fma_f32 v38, -v0, v34, v33
	v_fmac_f32_e32 v34, v38, v32
	v_fma_f32 v0, -v0, v34, v33
	v_div_fmas_f32 v0, v0, v32, v34
	v_div_fixup_f32 v31, v0, v31, 1.0
	v_div_scale_f32 v0, s[6:7], v30, v30, 1.0
	v_rcp_f32_e32 v32, v0
	s_nop 0
	v_fma_f32 v33, -v0, v32, 1.0
	v_fmac_f32_e32 v32, v33, v32
	v_div_scale_f32 v33, vcc, 1.0, v30, 1.0
	v_mul_f32_e32 v34, v33, v32
	v_fma_f32 v38, -v0, v34, v33
	v_fmac_f32_e32 v34, v38, v32
	v_fma_f32 v0, -v0, v34, v33
	v_div_fmas_f32 v0, v0, v32, v34
	v_div_fixup_f32 v30, v0, v30, 1.0
	v_mul_f32_e32 v0, 0xbfb8aa3b, v26
	v_exp_f32_e32 v26, v0
	v_mul_f32_e32 v0, 0xbfb8aa3b, v27
	v_exp_f32_e32 v27, v0
	v_lshlrev_b32_e32 v32, 16, v233
	v_and_b32_e32 v33, 0xffff0000, v233
	v_pk_fma_f32 v[116:117], v[30:31], v[32:33], v[116:117]
	v_pk_add_f32 v[26:27], v[26:27], 1.0 op_sel_hi:[1,0]
	s_nop 0
	v_div_scale_f32 v0, s[6:7], v27, v27, 1.0
	v_rcp_f32_e32 v30, v0
	s_nop 0
	v_fma_f32 v31, -v0, v30, 1.0
	v_fmac_f32_e32 v30, v31, v30
	v_div_scale_f32 v31, vcc, 1.0, v27, 1.0
	v_mul_f32_e32 v32, v31, v30
	v_fma_f32 v33, -v0, v32, v31
	v_fmac_f32_e32 v32, v33, v30
	v_fma_f32 v0, -v0, v32, v31
	v_div_fmas_f32 v0, v0, v30, v32
	v_div_fixup_f32 v27, v0, v27, 1.0
	v_div_scale_f32 v0, s[6:7], v26, v26, 1.0
	v_rcp_f32_e32 v30, v0
	s_nop 0
	v_fma_f32 v31, -v0, v30, 1.0
	v_fmac_f32_e32 v30, v31, v30
	v_div_scale_f32 v31, vcc, 1.0, v26, 1.0
	v_mul_f32_e32 v32, v31, v30
	v_fma_f32 v33, -v0, v32, v31
	v_fmac_f32_e32 v32, v33, v30
	v_fma_f32 v0, -v0, v32, v31
	v_div_fmas_f32 v0, v0, v30, v32
	v_div_fixup_f32 v26, v0, v26, 1.0
	v_lshlrev_b32_e32 v30, 16, v234
	v_and_b32_e32 v31, 0xffff0000, v234
	v_mul_f32_e32 v0, 0xbfb8aa3b, v28
	v_pk_fma_f32 v[110:111], v[26:27], v[30:31], v[110:111]
	v_exp_f32_e32 v26, v0
	v_mul_f32_e32 v0, 0xbfb8aa3b, v29
	v_exp_f32_e32 v27, v0
	s_nop 0
	v_pk_add_f32 v[26:27], v[26:27], 1.0 op_sel_hi:[1,0]
	s_nop 0
	v_div_scale_f32 v0, s[6:7], v27, v27, 1.0
	v_rcp_f32_e32 v28, v0
	s_nop 0
	v_fma_f32 v29, -v0, v28, 1.0
	v_fmac_f32_e32 v28, v29, v28
	v_div_scale_f32 v29, vcc, 1.0, v27, 1.0
	v_mul_f32_e32 v30, v29, v28
	v_fma_f32 v31, -v0, v30, v29
	v_fmac_f32_e32 v30, v31, v28
	v_fma_f32 v0, -v0, v30, v29
	v_div_fmas_f32 v0, v0, v28, v30
	v_div_fixup_f32 v27, v0, v27, 1.0
	v_div_scale_f32 v0, s[6:7], v26, v26, 1.0
	v_rcp_f32_e32 v28, v0
	s_nop 0
	v_fma_f32 v29, -v0, v28, 1.0
	v_fmac_f32_e32 v28, v29, v28
	v_div_scale_f32 v29, vcc, 1.0, v26, 1.0
	v_mul_f32_e32 v30, v29, v28
	v_fma_f32 v31, -v0, v30, v29
	v_fmac_f32_e32 v30, v31, v28
	v_fma_f32 v0, -v0, v30, v29
	v_div_fmas_f32 v0, v0, v28, v30
	v_div_fixup_f32 v26, v0, v26, 1.0
	v_lshlrev_b32_e32 v28, 16, v235
	v_and_b32_e32 v29, 0xffff0000, v235
	v_pk_fma_f32 v[112:113], v[26:27], v[28:29], v[112:113]
	v_mul_f32_e32 v0, 0xbfb8aa3b, v22
	v_exp_f32_e32 v22, v0
	v_mul_f32_e32 v0, 0xbfb8aa3b, v23
	v_exp_f32_e32 v23, v0
	s_nop 0
	v_pk_add_f32 v[22:23], v[22:23], 1.0 op_sel_hi:[1,0]
	s_nop 0
	v_div_scale_f32 v0, s[6:7], v23, v23, 1.0
	v_rcp_f32_e32 v30, v0
	s_nop 0
	v_fma_f32 v31, -v0, v30, 1.0
	v_fmac_f32_e32 v30, v31, v30
	v_div_scale_f32 v31, vcc, 1.0, v23, 1.0
	v_mul_f32_e32 v32, v31, v30
	v_fma_f32 v33, -v0, v32, v31
	v_fmac_f32_e32 v32, v33, v30
	v_fma_f32 v0, -v0, v32, v31
	v_div_fmas_f32 v0, v0, v30, v32
	v_div_fixup_f32 v23, v0, v23, 1.0
	v_div_scale_f32 v0, s[6:7], v22, v22, 1.0
	v_rcp_f32_e32 v30, v0
	s_nop 0
	v_fma_f32 v31, -v0, v30, 1.0
	v_fmac_f32_e32 v30, v31, v30
	v_div_scale_f32 v31, vcc, 1.0, v22, 1.0
	v_mul_f32_e32 v32, v31, v30
	v_fma_f32 v33, -v0, v32, v31
	v_fmac_f32_e32 v32, v33, v30
	v_fma_f32 v0, -v0, v32, v31
	v_div_fmas_f32 v0, v0, v30, v32
	v_div_fixup_f32 v22, v0, v22, 1.0
	v_mul_f32_e32 v0, 0xbfb8aa3b, v24
	s_waitcnt vmcnt(2) lgkmcnt(0)
	v_lshlrev_b32_e32 v30, 16, v236
	v_and_b32_e32 v31, 0xffff0000, v236
	v_pk_fma_f32 v[106:107], v[22:23], v[30:31], v[106:107]
	v_exp_f32_e32 v22, v0
	v_mul_f32_e32 v0, 0xbfb8aa3b, v25
	v_exp_f32_e32 v23, v0
	s_nop 0
	v_pk_add_f32 v[22:23], v[22:23], 1.0 op_sel_hi:[1,0]
	s_nop 0
	v_div_scale_f32 v0, s[6:7], v23, v23, 1.0
	v_rcp_f32_e32 v24, v0
	s_nop 0
	v_fma_f32 v25, -v0, v24, 1.0
	v_fmac_f32_e32 v24, v25, v24
	v_div_scale_f32 v25, vcc, 1.0, v23, 1.0
	v_mul_f32_e32 v26, v25, v24
	v_fma_f32 v30, -v0, v26, v25
	v_fmac_f32_e32 v26, v30, v24
	v_fma_f32 v0, -v0, v26, v25
	v_div_fmas_f32 v0, v0, v24, v26
	v_div_fixup_f32 v23, v0, v23, 1.0
	v_div_scale_f32 v0, s[6:7], v22, v22, 1.0
	v_rcp_f32_e32 v24, v0
	s_nop 0
	v_fma_f32 v25, -v0, v24, 1.0
	v_fmac_f32_e32 v24, v25, v24
	v_div_scale_f32 v25, vcc, 1.0, v22, 1.0
	v_mul_f32_e32 v26, v25, v24
	v_fma_f32 v30, -v0, v26, v25
	v_fmac_f32_e32 v26, v30, v24
	v_fma_f32 v0, -v0, v26, v25
	v_div_fmas_f32 v0, v0, v24, v26
	v_div_fixup_f32 v22, v0, v22, 1.0
	v_mul_f32_e32 v0, 0xbfb8aa3b, v18
	v_exp_f32_e32 v18, v0
	v_mul_f32_e32 v0, 0xbfb8aa3b, v19
	v_exp_f32_e32 v19, v0
	v_lshlrev_b32_e32 v24, 16, v237
	v_and_b32_e32 v25, 0xffff0000, v237
	v_pk_fma_f32 v[108:109], v[22:23], v[24:25], v[108:109]
	v_pk_add_f32 v[18:19], v[18:19], 1.0 op_sel_hi:[1,0]
	s_nop 0
	v_div_scale_f32 v0, s[6:7], v19, v19, 1.0
	v_rcp_f32_e32 v22, v0
	s_nop 0
	v_fma_f32 v23, -v0, v22, 1.0
	v_fmac_f32_e32 v22, v23, v22
; DEVI float bf2f(unsigned u) { return __uint_as_float(u << 16); }
; DEVI float sigmoidf(float x) { return 1.f / (1.f + __expf(-x)); }
; DEVI void phase_merge(const Params& p, char* smem) {
;     ...
; #pragma unroll
;       for (int m = 0; m < 4; ++m)
; #pragma unroll
;         for (int n = 0; n < 4; ++n) {
;           const u32x4 bq = brg[(m * 2 + (n >> 1)) * 256];
;           const unsigned b0 = bq[(n & 1) * 2], b1 = bq[(n & 1) * 2 + 1];
;           res[m][n][0] += sigmoidf(acc[m][n][0]) * bf2f(b0 & 0xffffu);
;           res[m][n][1] += sigmoidf(acc[m][n][1]) * __uint_as_float(b0 & 0xffff0000u);
;           res[m][n][2] += sigmoidf(acc[m][n][2]) * bf2f(b1 & 0xffffu);
;           res[m][n][3] += sigmoidf(acc[m][n][3]) * __uint_as_float(b1 & 0xffff0000u);
;         }
	v_div_scale_f32 v23, vcc, 1.0, v19, 1.0
	v_mul_f32_e32 v24, v23, v22
	v_fma_f32 v25, -v0, v24, v23
	v_fmac_f32_e32 v24, v25, v22
	v_fma_f32 v0, -v0, v24, v23
	v_div_fmas_f32 v0, v0, v22, v24
	v_div_fixup_f32 v19, v0, v19, 1.0
	v_div_scale_f32 v0, s[6:7], v18, v18, 1.0
	v_rcp_f32_e32 v22, v0
	s_nop 0
	v_fma_f32 v23, -v0, v22, 1.0
	v_fmac_f32_e32 v22, v23, v22
	v_div_scale_f32 v23, vcc, 1.0, v18, 1.0
	v_mul_f32_e32 v24, v23, v22
	v_fma_f32 v25, -v0, v24, v23
	v_fmac_f32_e32 v24, v25, v22
	v_fma_f32 v0, -v0, v24, v23
	v_div_fmas_f32 v0, v0, v22, v24
	v_div_fixup_f32 v18, v0, v18, 1.0
	v_lshlrev_b32_e32 v22, 16, v238
	v_and_b32_e32 v23, 0xffff0000, v238
	v_mul_f32_e32 v0, 0xbfb8aa3b, v20
	v_pk_fma_f32 v[102:103], v[18:19], v[22:23], v[102:103]
	v_exp_f32_e32 v18, v0
	v_mul_f32_e32 v0, 0xbfb8aa3b, v21
	v_exp_f32_e32 v19, v0
	s_nop 0
	v_pk_add_f32 v[18:19], v[18:19], 1.0 op_sel_hi:[1,0]
	s_nop 0
	v_div_scale_f32 v0, s[6:7], v19, v19, 1.0
	v_rcp_f32_e32 v20, v0
	s_nop 0
	v_fma_f32 v21, -v0, v20, 1.0
	v_fmac_f32_e32 v20, v21, v20
	v_div_scale_f32 v21, vcc, 1.0, v19, 1.0
	v_mul_f32_e32 v22, v21, v20
	v_fma_f32 v23, -v0, v22, v21
	v_fmac_f32_e32 v22, v23, v20
	v_fma_f32 v0, -v0, v22, v21
	v_div_fmas_f32 v0, v0, v20, v22
	v_div_fixup_f32 v19, v0, v19, 1.0
	v_div_scale_f32 v0, s[6:7], v18, v18, 1.0
	v_rcp_f32_e32 v20, v0
	s_nop 0
	v_fma_f32 v21, -v0, v20, 1.0
	v_fmac_f32_e32 v20, v21, v20
	v_div_scale_f32 v21, vcc, 1.0, v18, 1.0
	v_mul_f32_e32 v22, v21, v20
	v_fma_f32 v23, -v0, v22, v21
	v_fmac_f32_e32 v22, v23, v20
	v_fma_f32 v0, -v0, v22, v21
	v_div_fmas_f32 v0, v0, v20, v22
	v_div_fixup_f32 v18, v0, v18, 1.0
	v_lshlrev_b32_e32 v20, 16, v239
	v_and_b32_e32 v21, 0xffff0000, v239
	v_pk_fma_f32 v[104:105], v[18:19], v[20:21], v[104:105]
	v_mul_f32_e32 v0, 0xbfb8aa3b, v14
	v_exp_f32_e32 v14, v0
	v_mul_f32_e32 v0, 0xbfb8aa3b, v15
	v_exp_f32_e32 v15, v0
	s_nop 0
	v_pk_add_f32 v[14:15], v[14:15], 1.0 op_sel_hi:[1,0]
	s_nop 0
	v_div_scale_f32 v0, s[6:7], v15, v15, 1.0
	v_rcp_f32_e32 v22, v0
	s_nop 0
	v_fma_f32 v23, -v0, v22, 1.0
	v_fmac_f32_e32 v22, v23, v22
	v_div_scale_f32 v23, vcc, 1.0, v15, 1.0
	v_mul_f32_e32 v24, v23, v22
	v_fma_f32 v25, -v0, v24, v23
	v_fmac_f32_e32 v24, v25, v22
	v_fma_f32 v0, -v0, v24, v23
	v_div_fmas_f32 v0, v0, v22, v24
	v_div_fixup_f32 v15, v0, v15, 1.0
	v_div_scale_f32 v0, s[6:7], v14, v14, 1.0
	v_rcp_f32_e32 v22, v0
	s_nop 0
	v_fma_f32 v23, -v0, v22, 1.0
	v_fmac_f32_e32 v22, v23, v22
	v_div_scale_f32 v23, vcc, 1.0, v14, 1.0
	v_mul_f32_e32 v24, v23, v22
	v_fma_f32 v25, -v0, v24, v23
	v_fmac_f32_e32 v24, v25, v22
	v_fma_f32 v0, -v0, v24, v23
	v_div_fmas_f32 v0, v0, v22, v24
	v_div_fixup_f32 v14, v0, v14, 1.0
	v_mul_f32_e32 v0, 0xbfb8aa3b, v16
	s_waitcnt vmcnt(1) lgkmcnt(0)
	v_lshlrev_b32_e32 v22, 16, v240
	v_and_b32_e32 v23, 0xffff0000, v240
	v_pk_fma_f32 v[98:99], v[14:15], v[22:23], v[98:99]
	v_exp_f32_e32 v14, v0
	v_mul_f32_e32 v0, 0xbfb8aa3b, v17
	v_exp_f32_e32 v15, v0
	s_nop 0
	v_pk_add_f32 v[14:15], v[14:15], 1.0 op_sel_hi:[1,0]
	s_nop 0
	v_div_scale_f32 v0, s[6:7], v15, v15, 1.0
	v_rcp_f32_e32 v16, v0
	s_nop 0
	v_fma_f32 v17, -v0, v16, 1.0
	v_fmac_f32_e32 v16, v17, v16
	v_div_scale_f32 v17, vcc, 1.0, v15, 1.0
	v_mul_f32_e32 v18, v17, v16
	v_fma_f32 v22, -v0, v18, v17
	v_fmac_f32_e32 v18, v22, v16
	v_fma_f32 v0, -v0, v18, v17
	v_div_fmas_f32 v0, v0, v16, v18
	v_div_fixup_f32 v15, v0, v15, 1.0
	v_div_scale_f32 v0, s[6:7], v14, v14, 1.0
	v_rcp_f32_e32 v16, v0
	s_nop 0
	v_fma_f32 v17, -v0, v16, 1.0
	v_fmac_f32_e32 v16, v17, v16
	v_div_scale_f32 v17, vcc, 1.0, v14, 1.0
	v_mul_f32_e32 v18, v17, v16
	v_fma_f32 v22, -v0, v18, v17
	v_fmac_f32_e32 v18, v22, v16
	v_fma_f32 v0, -v0, v18, v17
	v_div_fmas_f32 v0, v0, v16, v18
	v_div_fixup_f32 v14, v0, v14, 1.0
	v_mul_f32_e32 v0, 0xbfb8aa3b, v10
	v_exp_f32_e32 v10, v0
	v_mul_f32_e32 v0, 0xbfb8aa3b, v11
	v_exp_f32_e32 v11, v0
	v_lshlrev_b32_e32 v16, 16, v241
	v_and_b32_e32 v17, 0xffff0000, v241
	v_pk_fma_f32 v[100:101], v[14:15], v[16:17], v[100:101]
	v_pk_add_f32 v[10:11], v[10:11], 1.0 op_sel_hi:[1,0]
	s_nop 0
	v_div_scale_f32 v0, s[6:7], v11, v11, 1.0
	v_rcp_f32_e32 v14, v0
	s_nop 0
	v_fma_f32 v15, -v0, v14, 1.0
	v_fmac_f32_e32 v14, v15, v14
	v_div_scale_f32 v15, vcc, 1.0, v11, 1.0
	v_mul_f32_e32 v16, v15, v14
	v_fma_f32 v17, -v0, v16, v15
	v_fmac_f32_e32 v16, v17, v14
	v_fma_f32 v0, -v0, v16, v15
	v_div_fmas_f32 v0, v0, v14, v16
	v_div_fixup_f32 v11, v0, v11, 1.0
	v_div_scale_f32 v0, s[6:7], v10, v10, 1.0
	v_rcp_f32_e32 v14, v0
	s_nop 0
	v_fma_f32 v15, -v0, v14, 1.0
	v_fmac_f32_e32 v14, v15, v14
	v_div_scale_f32 v15, vcc, 1.0, v10, 1.0
	v_mul_f32_e32 v16, v15, v14
	v_fma_f32 v17, -v0, v16, v15
	v_fmac_f32_e32 v16, v17, v14
	v_fma_f32 v0, -v0, v16, v15
	v_div_fmas_f32 v0, v0, v14, v16
	v_div_fixup_f32 v10, v0, v10, 1.0
	v_lshlrev_b32_e32 v14, 16, v242
	v_and_b32_e32 v15, 0xffff0000, v242
	v_mul_f32_e32 v0, 0xbfb8aa3b, v12
	v_pk_fma_f32 v[94:95], v[10:11], v[14:15], v[94:95]
	v_exp_f32_e32 v10, v0
	v_mul_f32_e32 v0, 0xbfb8aa3b, v13
	v_exp_f32_e32 v11, v0
	s_nop 0
	v_pk_add_f32 v[10:11], v[10:11], 1.0 op_sel_hi:[1,0]
	s_nop 0
	v_div_scale_f32 v0, s[6:7], v11, v11, 1.0
	v_rcp_f32_e32 v12, v0
	s_nop 0
	v_fma_f32 v13, -v0, v12, 1.0
	v_fmac_f32_e32 v12, v13, v12
	v_div_scale_f32 v13, vcc, 1.0, v11, 1.0
	v_mul_f32_e32 v14, v13, v12
	v_fma_f32 v15, -v0, v14, v13
	v_fmac_f32_e32 v14, v15, v12
	v_fma_f32 v0, -v0, v14, v13
	v_div_fmas_f32 v0, v0, v12, v14
	v_div_fixup_f32 v11, v0, v11, 1.0
	v_div_scale_f32 v0, s[6:7], v10, v10, 1.0
	v_rcp_f32_e32 v12, v0
	s_nop 0
	v_fma_f32 v13, -v0, v12, 1.0
	v_fmac_f32_e32 v12, v13, v12
	v_div_scale_f32 v13, vcc, 1.0, v10, 1.0
	v_mul_f32_e32 v14, v13, v12
	v_fma_f32 v15, -v0, v14, v13
	v_fmac_f32_e32 v14, v15, v12
	v_fma_f32 v0, -v0, v14, v13
	v_div_fmas_f32 v0, v0, v12, v14
	v_div_fixup_f32 v10, v0, v10, 1.0
	v_lshlrev_b32_e32 v12, 16, v243
	v_and_b32_e32 v13, 0xffff0000, v243
	v_pk_fma_f32 v[96:97], v[10:11], v[12:13], v[96:97]
	v_mul_f32_e32 v0, 0xbfb8aa3b, v6
	v_exp_f32_e32 v6, v0
	v_mul_f32_e32 v0, 0xbfb8aa3b, v7
	v_exp_f32_e32 v7, v0
	s_nop 0
	v_pk_add_f32 v[6:7], v[6:7], 1.0 op_sel_hi:[1,0]
	s_nop 0
	v_div_scale_f32 v0, s[6:7], v7, v7, 1.0
	v_rcp_f32_e32 v14, v0
	s_nop 0
	v_fma_f32 v15, -v0, v14, 1.0
	v_fmac_f32_e32 v14, v15, v14
	v_div_scale_f32 v15, vcc, 1.0, v7, 1.0
	v_mul_f32_e32 v16, v15, v14
	v_fma_f32 v17, -v0, v16, v15
	v_fmac_f32_e32 v16, v17, v14
	v_fma_f32 v0, -v0, v16, v15
	v_div_fmas_f32 v0, v0, v14, v16
	v_div_fixup_f32 v7, v0, v7, 1.0
	v_div_scale_f32 v0, s[6:7], v6, v6, 1.0
	v_rcp_f32_e32 v14, v0
	s_nop 0
	v_fma_f32 v15, -v0, v14, 1.0
	v_fmac_f32_e32 v14, v15, v14
	v_div_scale_f32 v15, vcc, 1.0, v6, 1.0
	v_mul_f32_e32 v16, v15, v14
	v_fma_f32 v17, -v0, v16, v15
	v_fmac_f32_e32 v16, v17, v14
	v_fma_f32 v0, -v0, v16, v15
	v_div_fmas_f32 v0, v0, v14, v16
	v_div_fixup_f32 v6, v0, v6, 1.0
	v_mul_f32_e32 v0, 0xbfb8aa3b, v8
	s_waitcnt vmcnt(0) lgkmcnt(0)
; DEVI float bf2f(unsigned u) { return __uint_as_float(u << 16); }
; DEVI float sigmoidf(float x) { return 1.f / (1.f + __expf(-x)); }
; DEVI void phase_merge(const Params& p, char* smem) {
;     ...
; #pragma unroll
;       for (int m = 0; m < 4; ++m)
; #pragma unroll
;         for (int n = 0; n < 4; ++n) {
;           const u32x4 bq = brg[(m * 2 + (n >> 1)) * 256];
;           const unsigned b0 = bq[(n & 1) * 2], b1 = bq[(n & 1) * 2 + 1];
;           res[m][n][0] += sigmoidf(acc[m][n][0]) * bf2f(b0 & 0xffffu);
;           res[m][n][1] += sigmoidf(acc[m][n][1]) * __uint_as_float(b0 & 0xffff0000u);
;           res[m][n][2] += sigmoidf(acc[m][n][2]) * bf2f(b1 & 0xffffu);
;           res[m][n][3] += sigmoidf(acc[m][n][3]) * __uint_as_float(b1 & 0xffff0000u);
;         }
	v_lshlrev_b32_e32 v14, 16, v244
	v_and_b32_e32 v15, 0xffff0000, v244
	v_pk_fma_f32 v[90:91], v[6:7], v[14:15], v[90:91]
	v_exp_f32_e32 v6, v0
	v_mul_f32_e32 v0, 0xbfb8aa3b, v9
	v_exp_f32_e32 v7, v0
	s_nop 0
	v_pk_add_f32 v[6:7], v[6:7], 1.0 op_sel_hi:[1,0]
	s_nop 0
	v_div_scale_f32 v0, s[6:7], v7, v7, 1.0
	v_rcp_f32_e32 v8, v0
	s_nop 0
	v_fma_f32 v9, -v0, v8, 1.0
	v_fmac_f32_e32 v8, v9, v8
	v_div_scale_f32 v9, vcc, 1.0, v7, 1.0
	v_mul_f32_e32 v10, v9, v8
	v_fma_f32 v14, -v0, v10, v9
	v_fmac_f32_e32 v10, v14, v8
	v_fma_f32 v0, -v0, v10, v9
	v_div_fmas_f32 v0, v0, v8, v10
	v_div_fixup_f32 v7, v0, v7, 1.0
	v_div_scale_f32 v0, s[6:7], v6, v6, 1.0
	v_rcp_f32_e32 v8, v0
	s_nop 0
	v_fma_f32 v9, -v0, v8, 1.0
	v_fmac_f32_e32 v8, v9, v8
	v_div_scale_f32 v9, vcc, 1.0, v6, 1.0
	v_mul_f32_e32 v10, v9, v8
	v_fma_f32 v14, -v0, v10, v9
	v_fmac_f32_e32 v10, v14, v8
	v_fma_f32 v0, -v0, v10, v9
	v_div_fmas_f32 v0, v0, v8, v10
	v_div_fixup_f32 v6, v0, v6, 1.0
	v_mul_f32_e32 v0, 0xbfb8aa3b, v2
	v_exp_f32_e32 v2, v0
	v_mul_f32_e32 v0, 0xbfb8aa3b, v3
	v_exp_f32_e32 v3, v0
	v_lshlrev_b32_e32 v8, 16, v245
	v_and_b32_e32 v9, 0xffff0000, v245
	v_pk_fma_f32 v[92:93], v[6:7], v[8:9], v[92:93]
	v_pk_add_f32 v[2:3], v[2:3], 1.0 op_sel_hi:[1,0]
	s_nop 0
	v_div_scale_f32 v0, s[6:7], v3, v3, 1.0
	v_rcp_f32_e32 v6, v0
	s_nop 0
	v_fma_f32 v7, -v0, v6, 1.0
	v_fmac_f32_e32 v6, v7, v6
	v_div_scale_f32 v7, vcc, 1.0, v3, 1.0
	v_mul_f32_e32 v8, v7, v6
	v_fma_f32 v9, -v0, v8, v7
	v_fmac_f32_e32 v8, v9, v6
	v_fma_f32 v0, -v0, v8, v7
	v_div_fmas_f32 v0, v0, v6, v8
	v_div_fixup_f32 v3, v0, v3, 1.0
	v_div_scale_f32 v0, s[6:7], v2, v2, 1.0
	v_rcp_f32_e32 v6, v0
	s_nop 0
	v_fma_f32 v7, -v0, v6, 1.0
	v_fmac_f32_e32 v6, v7, v6
	v_div_scale_f32 v7, vcc, 1.0, v2, 1.0
	v_mul_f32_e32 v8, v7, v6
	v_fma_f32 v9, -v0, v8, v7
	v_fmac_f32_e32 v8, v9, v6
	v_fma_f32 v0, -v0, v8, v7
	v_div_fmas_f32 v0, v0, v6, v8
	v_div_fixup_f32 v2, v0, v2, 1.0
	v_lshlrev_b32_e32 v6, 16, v246
	v_and_b32_e32 v7, 0xffff0000, v246
	v_mul_f32_e32 v0, 0xbfb8aa3b, v4
	v_pk_fma_f32 v[86:87], v[2:3], v[6:7], v[86:87]
	v_exp_f32_e32 v2, v0
	v_mul_f32_e32 v0, 0xbfb8aa3b, v5
	v_exp_f32_e32 v3, v0
	s_nop 0
	v_pk_add_f32 v[2:3], v[2:3], 1.0 op_sel_hi:[1,0]
	s_nop 0
	v_div_scale_f32 v0, s[6:7], v3, v3, 1.0
	v_rcp_f32_e32 v4, v0
	s_nop 0
	v_fma_f32 v5, -v0, v4, 1.0
	v_fmac_f32_e32 v4, v5, v4
	v_div_scale_f32 v5, vcc, 1.0, v3, 1.0
	v_mul_f32_e32 v6, v5, v4
	v_fma_f32 v7, -v0, v6, v5
	v_fmac_f32_e32 v6, v7, v4
	v_fma_f32 v0, -v0, v6, v5
	v_div_fmas_f32 v0, v0, v4, v6
	v_div_fixup_f32 v3, v0, v3, 1.0
	v_div_scale_f32 v0, s[6:7], v2, v2, 1.0
	v_rcp_f32_e32 v4, v0
	s_nop 0
	v_fma_f32 v5, -v0, v4, 1.0
	v_fmac_f32_e32 v4, v5, v4
	v_div_scale_f32 v5, vcc, 1.0, v2, 1.0
	v_mul_f32_e32 v6, v5, v4
	v_fma_f32 v7, -v0, v6, v5
	v_fmac_f32_e32 v6, v7, v4
	v_fma_f32 v0, -v0, v6, v5
	v_div_fmas_f32 v0, v0, v4, v6
	v_div_fixup_f32 v2, v0, v2, 1.0
	v_lshlrev_b32_e32 v4, 16, v247
	v_and_b32_e32 v5, 0xffff0000, v247
	v_pk_fma_f32 v[88:89], v[2:3], v[4:5], v[88:89]
	s_cbranch_scc1 .LBB0_1422
